# attention fast path: exp/pack per 32-key chunk with that chunk's PV MFMAs and V reads issued under the next chunk's VALU work
# baseline (speedup 1.0000x reference)
.Lattn_fast:
	v_add_u32_e32 v241, s4, v159
	v_add_u32_e32 v201, v241, v161
	ds_read_b128 v[220:223], v201
	ds_read_b128 v[224:227], v201 offset:64
	ds_read_b128 v[228:231], v201 offset:2304
	ds_read_b128 v[232:235], v201 offset:2368
	ds_read_b128 v[236:239], v201 offset:4608
	ds_read_b128 v[252:255], v201 offset:4672
	s_waitcnt lgkmcnt(4)
	v_mfma_f32_16x16x32_bf16 v[40:43], v[220:223], v[16:19], 0
	v_mfma_f32_16x16x32_bf16 v[40:43], v[224:227], v[20:23], v[40:43]
	ds_read_b128 v[220:223], v201 offset:6912
	ds_read_b128 v[224:227], v201 offset:6976
	s_waitcnt lgkmcnt(4)
	v_mfma_f32_16x16x32_bf16 v[44:47], v[228:231], v[16:19], 0
	v_mfma_f32_16x16x32_bf16 v[44:47], v[232:235], v[20:23], v[44:47]
	ds_read_b128 v[228:231], v201 offset:9216
	ds_read_b128 v[232:235], v201 offset:9280
	s_waitcnt lgkmcnt(4)
	v_mfma_f32_16x16x32_bf16 v[48:51], v[236:239], v[16:19], 0
	v_mfma_f32_16x16x32_bf16 v[48:51], v[252:255], v[20:23], v[48:51]
	ds_read_b128 v[236:239], v201 offset:11520
	ds_read_b128 v[252:255], v201 offset:11584
	s_waitcnt lgkmcnt(4)
	v_mfma_f32_16x16x32_bf16 v[52:55], v[220:223], v[16:19], 0
	v_mfma_f32_16x16x32_bf16 v[52:55], v[224:227], v[20:23], v[52:55]
	ds_read_b128 v[220:223], v201 offset:13824
	ds_read_b128 v[224:227], v201 offset:13888
	s_waitcnt lgkmcnt(4)
	v_mfma_f32_16x16x32_bf16 v[56:59], v[228:231], v[16:19], 0
	v_mfma_f32_16x16x32_bf16 v[56:59], v[232:235], v[20:23], v[56:59]
	ds_read_b128 v[228:231], v201 offset:16128
	ds_read_b128 v[232:235], v201 offset:16192
	s_waitcnt lgkmcnt(4)
	v_mfma_f32_16x16x32_bf16 v[60:63], v[236:239], v[16:19], 0
	v_mfma_f32_16x16x32_bf16 v[60:63], v[252:255], v[20:23], v[60:63]
	s_waitcnt lgkmcnt(2)
	v_mfma_f32_16x16x32_bf16 v[64:67], v[220:223], v[16:19], 0
	v_mfma_f32_16x16x32_bf16 v[64:67], v[224:227], v[20:23], v[64:67]
	s_waitcnt lgkmcnt(0)
	v_mfma_f32_16x16x32_bf16 v[68:71], v[228:231], v[16:19], 0
	v_mfma_f32_16x16x32_bf16 v[68:71], v[232:235], v[20:23], v[68:71]
	s_nop 7
	v_max3_f32 v200, v40, v41, s68
	v_max3_f32 v202, v42, v43, s68
	v_max3_f32 v200, v200, v44, v45
	v_max3_f32 v202, v202, v46, v47
	v_max3_f32 v200, v200, v48, v49
	v_max3_f32 v202, v202, v50, v51
	v_max3_f32 v200, v200, v52, v53
	v_max3_f32 v202, v202, v54, v55
	v_max3_f32 v200, v200, v56, v57
	v_max3_f32 v202, v202, v58, v59
	v_max3_f32 v200, v200, v60, v61
	v_max3_f32 v202, v202, v62, v63
	v_max3_f32 v200, v200, v64, v65
	v_max3_f32 v202, v202, v66, v67
	v_max3_f32 v200, v200, v68, v69
	v_max3_f32 v202, v202, v70, v71
	v_max_f32_e32 v200, v200, v202
	ds_bpermute_b32 v72, v195, v200
	v_max_f32_e32 v151, v200, v200
	s_waitcnt lgkmcnt(0)
	v_max_f32_e32 v72, v72, v72
	v_max_f32_e32 v72, v151, v72
	ds_bpermute_b32 v151, v196, v72
	s_waitcnt lgkmcnt(0)
	v_max3_f32 v151, v153, v72, v151
	v_sub_f32_e32 v72, v153, v151
	v_exp_f32_e32 v72, v72
	v_lshl_add_u32 v241, v160, 1, s38
	v_add_u32_e32 v241, v241, v162
	v_mul_f32_e32 v149, v149, v72
	v_pk_mul_f32 v[38:39], v[38:39], v[72:73] op_sel_hi:[1,0]
	v_pk_mul_f32 v[36:37], v[36:37], v[72:73] op_sel_hi:[1,0]
	v_pk_mul_f32 v[34:35], v[34:35], v[72:73] op_sel_hi:[1,0]
	v_pk_mul_f32 v[32:33], v[32:33], v[72:73] op_sel_hi:[1,0]
	v_pk_mul_f32 v[30:31], v[30:31], v[72:73] op_sel_hi:[1,0]
	v_pk_mul_f32 v[28:29], v[28:29], v[72:73] op_sel_hi:[1,0]
	v_pk_mul_f32 v[26:27], v[26:27], v[72:73] op_sel_hi:[1,0]
	v_pk_mul_f32 v[24:25], v[24:25], v[72:73] op_sel_hi:[1,0]
	ds_read_b64_tr_b16 v[220:221], v241
	ds_read_b64_tr_b16 v[222:223], v241 offset:2304
	ds_read_b64_tr_b16 v[224:225], v241 offset:32
	ds_read_b64_tr_b16 v[226:227], v241 offset:2336
	ds_read_b64_tr_b16 v[228:229], v241 offset:64
	ds_read_b64_tr_b16 v[230:231], v241 offset:2368
	ds_read_b64_tr_b16 v[232:233], v241 offset:96
	ds_read_b64_tr_b16 v[234:235], v241 offset:2400
	ds_read_b64_tr_b16 v[236:237], v241 offset:4608
	ds_read_b64_tr_b16 v[238:239], v241 offset:6912
	ds_read_b64_tr_b16 v[252:253], v241 offset:4640
	ds_read_b64_tr_b16 v[254:255], v241 offset:6944
	v_sub_f32_e32 v40, v40, v151
	v_sub_f32_e32 v41, v41, v151
	v_sub_f32_e32 v42, v42, v151
	v_sub_f32_e32 v43, v43, v151
	v_sub_f32_e32 v44, v44, v151
	v_sub_f32_e32 v45, v45, v151
	v_sub_f32_e32 v46, v46, v151
	v_sub_f32_e32 v47, v47, v151
	v_exp_f32_e32 v40, v40
	v_exp_f32_e32 v41, v41
	v_exp_f32_e32 v42, v42
	v_exp_f32_e32 v43, v43
	v_exp_f32_e32 v44, v44
	v_exp_f32_e32 v45, v45
	v_exp_f32_e32 v46, v46
	v_exp_f32_e32 v47, v47
	v_add_f32_e32 v149, v40, v149
	v_add_f32_e32 v149, v41, v149
	v_add_f32_e32 v149, v42, v149
	v_add_f32_e32 v149, v43, v149
	v_add_f32_e32 v149, v44, v149
	v_add_f32_e32 v149, v45, v149
	v_add_f32_e32 v149, v46, v149
	v_add_f32_e32 v149, v47, v149
	v_cvt_pk_bf16_f32 v40, v40, v41
	v_cvt_pk_bf16_f32 v41, v42, v43
	v_cvt_pk_bf16_f32 v42, v44, v45
	v_cvt_pk_bf16_f32 v43, v46, v47
	s_nop 1
	s_waitcnt lgkmcnt(10)
	v_mfma_f32_16x16x32_bf16 v[36:39], v[220:223], v[40:43], v[36:39]
	ds_read_b64_tr_b16 v[220:221], v241 offset:4672
	ds_read_b64_tr_b16 v[222:223], v241 offset:6976
	s_waitcnt lgkmcnt(10)
	v_mfma_f32_16x16x32_bf16 v[32:35], v[224:227], v[40:43], v[32:35]
	ds_read_b64_tr_b16 v[224:225], v241 offset:4704
	ds_read_b64_tr_b16 v[226:227], v241 offset:7008
	s_waitcnt lgkmcnt(10)
	v_mfma_f32_16x16x32_bf16 v[28:31], v[228:231], v[40:43], v[28:31]
	ds_read_b64_tr_b16 v[228:229], v241 offset:9216
	ds_read_b64_tr_b16 v[230:231], v241 offset:11520
	s_waitcnt lgkmcnt(10)
	v_mfma_f32_16x16x32_bf16 v[24:27], v[232:235], v[40:43], v[24:27]
	ds_read_b64_tr_b16 v[232:233], v241 offset:9248
	ds_read_b64_tr_b16 v[234:235], v241 offset:11552
	v_sub_f32_e32 v48, v48, v151
	v_sub_f32_e32 v49, v49, v151
	v_sub_f32_e32 v50, v50, v151
	v_sub_f32_e32 v51, v51, v151
	v_sub_f32_e32 v52, v52, v151
	v_sub_f32_e32 v53, v53, v151
	v_sub_f32_e32 v54, v54, v151
	v_sub_f32_e32 v55, v55, v151
	v_exp_f32_e32 v48, v48
	v_exp_f32_e32 v49, v49
	v_exp_f32_e32 v50, v50
	v_exp_f32_e32 v51, v51
	v_exp_f32_e32 v52, v52
	v_exp_f32_e32 v53, v53
	v_exp_f32_e32 v54, v54
	v_exp_f32_e32 v55, v55
	v_add_f32_e32 v149, v48, v149
	v_add_f32_e32 v149, v49, v149
	v_add_f32_e32 v149, v50, v149
	v_add_f32_e32 v149, v51, v149
	v_add_f32_e32 v149, v52, v149
	v_add_f32_e32 v149, v53, v149
	v_add_f32_e32 v149, v54, v149
	v_add_f32_e32 v149, v55, v149
	v_cvt_pk_bf16_f32 v48, v48, v49
	v_cvt_pk_bf16_f32 v49, v50, v51
	v_cvt_pk_bf16_f32 v50, v52, v53
	v_cvt_pk_bf16_f32 v51, v54, v55
	s_nop 1
	s_waitcnt lgkmcnt(10)
	v_mfma_f32_16x16x32_bf16 v[36:39], v[236:239], v[48:51], v[36:39]
	ds_read_b64_tr_b16 v[236:237], v241 offset:9280
	ds_read_b64_tr_b16 v[238:239], v241 offset:11584
	s_waitcnt lgkmcnt(10)
	v_mfma_f32_16x16x32_bf16 v[32:35], v[252:255], v[48:51], v[32:35]
	ds_read_b64_tr_b16 v[252:253], v241 offset:9312
	ds_read_b64_tr_b16 v[254:255], v241 offset:11616
	s_waitcnt lgkmcnt(10)
	v_mfma_f32_16x16x32_bf16 v[28:31], v[220:223], v[48:51], v[28:31]
	ds_read_b64_tr_b16 v[220:221], v241 offset:13824
	ds_read_b64_tr_b16 v[222:223], v241 offset:16128
	s_waitcnt lgkmcnt(10)
	v_mfma_f32_16x16x32_bf16 v[24:27], v[224:227], v[48:51], v[24:27]
	ds_read_b64_tr_b16 v[224:225], v241 offset:13856
	ds_read_b64_tr_b16 v[226:227], v241 offset:16160
	v_sub_f32_e32 v56, v56, v151
	v_sub_f32_e32 v57, v57, v151
	v_sub_f32_e32 v58, v58, v151
	v_sub_f32_e32 v59, v59, v151
	v_sub_f32_e32 v60, v60, v151
	v_sub_f32_e32 v61, v61, v151
	v_sub_f32_e32 v62, v62, v151
	v_sub_f32_e32 v63, v63, v151
	v_exp_f32_e32 v56, v56
	v_exp_f32_e32 v57, v57
	v_exp_f32_e32 v58, v58
	v_exp_f32_e32 v59, v59
	v_exp_f32_e32 v60, v60
	v_exp_f32_e32 v61, v61
	v_exp_f32_e32 v62, v62
	v_exp_f32_e32 v63, v63
	v_add_f32_e32 v149, v56, v149
	v_add_f32_e32 v149, v57, v149
	v_add_f32_e32 v149, v58, v149
	v_add_f32_e32 v149, v59, v149
	v_add_f32_e32 v149, v60, v149
	v_add_f32_e32 v149, v61, v149
	v_add_f32_e32 v149, v62, v149
	v_add_f32_e32 v149, v63, v149
	v_cvt_pk_bf16_f32 v56, v56, v57
	v_cvt_pk_bf16_f32 v57, v58, v59
	v_cvt_pk_bf16_f32 v58, v60, v61
	v_cvt_pk_bf16_f32 v59, v62, v63
	s_nop 1
	s_waitcnt lgkmcnt(10)
	v_mfma_f32_16x16x32_bf16 v[36:39], v[228:231], v[56:59], v[36:39]
	ds_read_b64_tr_b16 v[228:229], v241 offset:13888
	ds_read_b64_tr_b16 v[230:231], v241 offset:16192
	s_waitcnt lgkmcnt(10)
	v_mfma_f32_16x16x32_bf16 v[32:35], v[232:235], v[56:59], v[32:35]
	ds_read_b64_tr_b16 v[232:233], v241 offset:13920
	ds_read_b64_tr_b16 v[234:235], v241 offset:16224
	s_waitcnt lgkmcnt(10)
	v_mfma_f32_16x16x32_bf16 v[28:31], v[236:239], v[56:59], v[28:31]
	s_waitcnt lgkmcnt(8)
	v_mfma_f32_16x16x32_bf16 v[24:27], v[252:255], v[56:59], v[24:27]
	v_sub_f32_e32 v64, v64, v151
	v_sub_f32_e32 v65, v65, v151
	v_sub_f32_e32 v66, v66, v151
	v_sub_f32_e32 v67, v67, v151
	v_sub_f32_e32 v68, v68, v151
	v_sub_f32_e32 v69, v69, v151
	v_sub_f32_e32 v70, v70, v151
	v_sub_f32_e32 v71, v71, v151
	v_exp_f32_e32 v64, v64
	v_exp_f32_e32 v65, v65
	v_exp_f32_e32 v66, v66
	v_exp_f32_e32 v67, v67
	v_exp_f32_e32 v68, v68
	v_exp_f32_e32 v69, v69
	v_exp_f32_e32 v70, v70
	v_exp_f32_e32 v71, v71
	v_add_f32_e32 v149, v64, v149
	v_add_f32_e32 v149, v65, v149
	v_add_f32_e32 v149, v66, v149
	v_add_f32_e32 v149, v67, v149
	v_add_f32_e32 v149, v68, v149
	v_add_f32_e32 v149, v69, v149
	v_add_f32_e32 v149, v70, v149
	v_add_f32_e32 v149, v71, v149
	v_cvt_pk_bf16_f32 v64, v64, v65
	v_cvt_pk_bf16_f32 v65, v66, v67
	v_cvt_pk_bf16_f32 v66, v68, v69
	v_cvt_pk_bf16_f32 v67, v70, v71
	s_nop 1
	s_waitcnt lgkmcnt(6)
	v_mfma_f32_16x16x32_bf16 v[36:39], v[220:223], v[64:67], v[36:39]
	s_waitcnt lgkmcnt(4)
	v_mfma_f32_16x16x32_bf16 v[32:35], v[224:227], v[64:67], v[32:35]
	s_waitcnt lgkmcnt(2)
	v_mfma_f32_16x16x32_bf16 v[28:31], v[228:231], v[64:67], v[28:31]
	s_waitcnt lgkmcnt(0)
	v_mfma_f32_16x16x32_bf16 v[24:27], v[232:235], v[64:67], v[24:27]
	s_nop 7
	s_branch .LBB0_1170
